# chain: waves 0-3 issue their next-step LDS-DMA pieces at the step top, waves 4-7 after the 24th MFMA (DMA path overlapped with the other half's compute)
# baseline (speedup 1.0000x reference)
; #define LAS __attribute__((address_space(3)))
; #define RD_QD(dst, s0) _Pragma("unroll") for (int s_ = 0; s_ < 4; ++s_) { dst[s_] = *(const LAS bf16x8*)(B + CH_QD + i0 * 256 + (((2 * ((s0) + s_) + hi) ^ (i0 & 15)) << 4)); \
;                 dst[4 + s_] = *(const LAS bf16x8*)(B + CH_QD + i1 * 256 + (((2 * ((s0) + s_) + hi) ^ (i1 & 15)) << 4)); }
; #define DECAY(db_) do { f32x4 dc_[4]; _Pragma("unroll") for (int a4_ = 0; a4_ < 4; ++a4_) dc_[a4_] = *(const LAS f32x4*)(B + CH_DEC + ((db_) * 32 + 8 * a4_ + 4 * hi) * 4); \
;                 _Pragma("unroll") for (int a4_ = 0; a4_ < 4; ++a4_) _Pragma("unroll") for (int b4_ = 0; b4_ < 4; ++b4_) T[db_][a4_ * 4 + b4_] *= dc_[a4_][b4_]; } while (0)
; DI void phase_gla_chain(const Params& P, int l, int task0, int ntask_stride, LAS unsigned char* lds) {
;     ...
;             RD_QD(fa, 0);
; #pragma unroll
;             for (int ks = 0; ks < 4; ++ks) vf[ks] = *(const LAS bf16x8*)(B + CH_VT + vv * 128 + (((2 * ks + hi) ^ ((vv >> 1) & 7)) << 4));
;             __builtin_amdgcn_sched_barrier(0);
;             RD_QD(fb, 4);
;             __builtin_amdgcn_sched_barrier(0);
;             MM_QD(fa, 0);
;             DECAY(0); DECAY(1);
;             __builtin_amdgcn_sched_barrier(0);
; #pragma unroll
;             for (int ks = 0; ks < 4; ++ks) { fa[ks] = *(const LAS bf16x8*)(B + CH_AM + i0 * 128 + (((2 * ks + hi) ^ ((i0 >> 1) & 7)) << 4)); fa[4 + ks] = *(const LAS bf16x8*)(B + CH_AM + i1 * 128 + (((2 * ks + hi) ^ ((i1 >> 1) & 7)) << 4)); }
;             __builtin_amdgcn_sched_barrier(0);
;             MM_QD(fb, 4);
;             DECAY(2); DECAY(3);
;             __builtin_amdgcn_sched_barrier(0);
.LBB0_409:
	s_mul_i32 s92, s92, 0x12400
	s_add_i32 s22, s92, 0
	v_add_u32_e32 v74, s22, v205
	v_add_u32_e32 v75, s22, v141
	v_add_u32_e32 v66, v74, v149
	v_add_u32_e32 v70, v75, v149
	v_add_u32_e32 v76, v74, v151
	ds_read_b128 v[66:69], v66
	ds_read_b128 v[70:73], v70
	v_add_u32_e32 v77, v75, v151
	ds_read_b128 v[182:185], v76
	ds_read_b128 v[186:189], v77
	v_add_u32_e32 v76, v74, v153
	v_add_u32_e32 v77, v75, v153
	ds_read_b128 v[190:193], v76
	ds_read_b128 v[194:197], v77
	v_add_u32_e32 v76, v74, v160
	v_add_u32_e32 v77, v75, v160
	ds_read_b128 v[198:201], v76
	ds_read_b128 v[208:211], v77
	v_add_u32_e32 v76, s22, v173
	v_add_u32_e32 v77, v76, v162
	v_add_u32_e32 v78, v76, v164
	ds_read_b128 v[110:113], v77 offset:40960
	ds_read_b128 v[106:109], v78 offset:40960
	v_add_u32_e32 v77, v76, v165
	v_add_u32_e32 v76, v76, v166
	ds_read_b128 v[102:105], v77 offset:40960
	ds_read_b128 v[98:101], v76 offset:40960
	v_add_u32_e32 v76, v74, v167
	v_add_u32_e32 v77, v75, v167
	ds_read_b128 v[212:215], v76
	ds_read_b128 v[216:219], v77
	v_add_u32_e32 v76, v74, v168
	v_add_u32_e32 v77, v75, v168
	ds_read_b128 v[220:223], v76
	ds_read_b128 v[130:133], v77
	v_add_u32_e32 v76, v74, v169
	v_add_u32_e32 v74, v74, v170
	v_add_u32_e32 v77, v75, v169
	ds_read_b128 v[126:129], v76
	ds_read_b128 v[122:125], v77
	v_add_u32_e32 v75, v75, v170
	ds_read_b128 v[118:121], v74
	ds_read_b128 v[114:117], v75
	v_cvt_pk_bf16_f32 v74, v2, v3
	v_cvt_pk_bf16_f32 v75, v4, v5
	v_cvt_pk_bf16_f32 v76, v6, v7
	v_cvt_pk_bf16_f32 v77, v8, v9
	v_cvt_pk_bf16_f32 v224, v10, v11
	v_cvt_pk_bf16_f32 v225, v12, v13
	s_waitcnt lgkmcnt(0)
	v_mfma_f32_32x32x16_bf16 v[82:97], v[66:69], v[74:77], 0
	v_cvt_pk_bf16_f32 v226, v14, v15
	v_cvt_pk_bf16_f32 v227, v16, v17
	v_add_u32_e32 v207, s22, v146
	v_add_u32_e32 v231, 0x12000, v207
	v_cvt_pk_bf16_f32 v228, v26, v27
	v_cvt_pk_bf16_f32 v229, v28, v29
	v_cvt_pk_bf16_f32 v230, v30, v31
	v_mfma_f32_32x32x16_bf16 v[66:81], v[70:73], v[74:77], 0
	v_mfma_f32_32x32x16_bf16 v[82:97], v[182:185], v[224:227], v[82:97]
	v_cvt_pk_bf16_f32 v182, v18, v19
	v_cvt_pk_bf16_f32 v183, v20, v21
	v_cvt_pk_bf16_f32 v184, v22, v23
	v_cvt_pk_bf16_f32 v185, v24, v25
	v_mfma_f32_32x32x16_bf16 v[66:81], v[186:189], v[224:227], v[66:81]
	ds_read_b128 v[186:189], v231 offset:64
	ds_read_b128 v[224:227], v231 offset:96
	ds_read_b128 v[232:235], v231
	ds_read_b128 v[236:239], v231 offset:32
	v_cvt_pk_bf16_f32 v231, v32, v33
	s_waitcnt lgkmcnt(0)
	v_pk_mul_f32 v[10:11], v[10:11], v[186:187]
	v_pk_mul_f32 v[12:13], v[12:13], v[188:189]
	v_pk_mul_f32 v[14:15], v[14:15], v[224:225]
	v_pk_mul_f32 v[6:7], v[6:7], v[236:237]
	v_pk_mul_f32 v[16:17], v[16:17], v[226:227]
	v_mfma_f32_32x32x16_bf16 v[82:97], v[190:193], v[182:185], v[82:97]
	v_mul_f32_e64 v8, v8, v238
	v_mul_f32_e64 v9, v9, v239
	v_mul_f32_e64 v4, v4, v234
	v_mul_f32_e64 v5, v5, v235
	v_mul_f32_e64 v2, v2, v232
	v_mul_f32_e64 v3, v3, v233
	v_mfma_f32_32x32x16_bf16 v[66:81], v[194:197], v[182:185], v[66:81]
	v_add_u32_e32 v194, 0x12080, v207
	ds_read_b128 v[182:185], v194 offset:64
	ds_read_b128 v[186:189], v194 offset:96
	ds_read_b128 v[190:193], v194
	ds_read_b128 v[194:197], v194 offset:32
	s_waitcnt lgkmcnt(0)
	v_pk_mul_f32 v[26:27], v[26:27], v[182:183]
	v_pk_mul_f32 v[30:31], v[30:31], v[186:187]
	v_pk_mul_f32 v[32:33], v[32:33], v[188:189]
	v_pk_mul_f32 v[22:23], v[22:23], v[194:195]
	v_pk_mul_f32 v[28:29], v[28:29], v[184:185]
	v_pk_mul_f32 v[24:25], v[24:25], v[196:197]
	v_pk_mul_f32 v[20:21], v[20:21], v[192:193]
	v_pk_mul_f32 v[18:19], v[18:19], v[190:191]
	v_mfma_f32_32x32x16_bf16 v[82:97], v[198:201], v[228:231], v[82:97]
	v_mfma_f32_32x32x16_bf16 v[66:81], v[208:211], v[228:231], v[66:81]
	v_add_u32_e32 v224, s22, v143
	v_add_u32_e32 v225, s22, v145
	v_add_u32_e32 v240, v224, v162
	v_add_u32_e32 v186, v225, v162
	v_add_u32_e32 v241, v224, v164
	v_add_u32_e32 v194, v225, v164
	v_add_u32_e32 v242, v224, v165
	v_add_u32_e32 v208, v225, v165
	v_add_u32_e32 v243, v224, v166
	v_add_u32_e32 v228, v225, v166
	ds_read_b128 v[182:185], v240 offset:16384
	ds_read_b128 v[186:189], v186 offset:16384
	ds_read_b128 v[190:193], v241 offset:16384
	ds_read_b128 v[194:197], v194 offset:16384
	ds_read_b128 v[198:201], v242 offset:16384
	ds_read_b128 v[208:211], v208 offset:16384
	ds_read_b128 v[224:227], v243 offset:16384
	ds_read_b128 v[228:231], v228 offset:16384
	v_cvt_pk_bf16_f32 v232, v34, v35
	v_cvt_pk_bf16_f32 v233, v36, v37
	v_cvt_pk_bf16_f32 v234, v38, v39
	v_cvt_pk_bf16_f32 v235, v40, v41
	s_nop 1
	v_mfma_f32_32x32x16_bf16 v[82:97], v[212:215], v[232:235], v[82:97]
	v_cvt_pk_bf16_f32 v212, v42, v43
	v_cvt_pk_bf16_f32 v213, v44, v45
	v_cvt_pk_bf16_f32 v214, v46, v47
	v_cvt_pk_bf16_f32 v215, v48, v49
	v_mfma_f32_32x32x16_bf16 v[66:81], v[216:219], v[232:235], v[66:81]
	v_cvt_pk_bf16_f32 v216, v50, v51
	v_cvt_pk_bf16_f32 v217, v52, v53
	v_cvt_pk_bf16_f32 v218, v54, v55
	v_cvt_pk_bf16_f32 v219, v56, v57
	v_mfma_f32_32x32x16_bf16 v[82:97], v[220:223], v[212:215], v[82:97]
	v_add_u32_e32 v223, 0x12100, v207
	v_add_u32_e32 v207, 0x12180, v207
	v_cvt_pk_bf16_f32 v220, v58, v59
	v_cvt_pk_bf16_f32 v221, v60, v61
	v_cvt_pk_bf16_f32 v222, v62, v63
	v_mfma_f32_32x32x16_bf16 v[66:81], v[130:133], v[212:215], v[66:81]
	ds_read_b128 v[130:133], v223 offset:64
	ds_read_b128 v[212:215], v223 offset:96
	ds_read_b128 v[232:235], v223
	ds_read_b128 v[236:239], v223 offset:32
	v_cvt_pk_bf16_f32 v223, v64, v65
	s_waitcnt lgkmcnt(0)
; DI int crow(int r, int hi) { return (r & 3) + 8 * (r >> 2) + 4 * hi; }
; DI unsigned pkbf(float a, float b) { f32x2 v = {a, b}; bfx2 r = __builtin_convertvector(v, bfx2); return __builtin_bit_cast(unsigned, r); }
; #define RD_KT(dst, db0) _Pragma("unroll") for (int q_ = 0; q_ < 2; ++q_) { const int d_ = ((db0) + q_) * 32 + r32; \
;                 _Pragma("unroll") for (int ks_ = 0; ks_ < 4; ++ks_) dst[q_ * 4 + ks_] = *(const LAS bf16x8*)(B + CH_KT + d_ * 128 + (((2 * ks_ + hi) ^ ((d_ >> 1) & 7)) << 4)); }
; #define MM_KT(src, db0) _Pragma("unroll") for (int q_ = 0; q_ < 2; ++q_) { \
;                 _Pragma("unroll") for (int ks_ = 0; ks_ < 4; ++ks_) T[(db0) + q_] = __builtin_amdgcn_mfma_f32_32x32x16_bf16(src[q_ * 4 + ks_], vf[ks_], T[(db0) + q_], 0, 0, 0); }
; DI void phase_gla_chain(const Params& P, int l, int task0, int ntask_stride, LAS unsigned char* lds) {
;     ...
;             MM_QD(fb, 4);
;             DECAY(2); DECAY(3);
;             __builtin_amdgcn_sched_barrier(0);
;             RD_KT(fb, 0);
;             __builtin_amdgcn_sched_barrier(0);
; #pragma unroll
;             for (int ks = 0; ks < 4; ++ks) { o[0] = __builtin_amdgcn_mfma_f32_32x32x16_bf16(fa[ks], vf[ks], o[0], 0, 0, 0); o[1] = __builtin_amdgcn_mfma_f32_32x32x16_bf16(fa[4 + ks], vf[ks], o[1], 0, 0, 0); }
;             __builtin_amdgcn_sched_barrier(0);
;             RD_KT(fa, 2);
;             __builtin_amdgcn_sched_barrier(0);
;             MM_KT(fb, 0);
;             __builtin_amdgcn_sched_barrier(0);
;             MM_KT(fa, 2);
;     ...
;             { const int cs = dir ? 63 - n : n; const size_t tokb = (size_t)sq * SEQL + cs * 64; const int odd = lane & 1;
;               bf16_t* ob = OFB + (size_t)dir * MTOK * 1024 + h * 256 + wid * 32 + (r32 & ~1);
; #pragma unroll
;               for (int ib = 0; ib < 2; ++ib)
; #pragma unroll
;                   for (int x = 0; x < 16; x += 2) { float ea_ = o[ib][x], eb_ = o[ib][x + 1]; asm volatile("" : "+v"(ea_), "+v"(eb_)); const float mine = odd ? eb_ : ea_, give = odd ? ea_ : eb_;
;                       const float got = __int_as_float(__builtin_amdgcn_update_dpp(0, __float_as_int(give), 0xB1, 0xF, 0xF, true));
;                       const unsigned w = odd ? pkbf(got, mine) : pkbf(mine, got);
;                       *(unsigned*)(ob + (tokb + ib * 32 + crow(x + odd, hi)) * 1024) = w; } }
	v_pk_mul_f32 v[42:43], v[42:43], v[130:131]
	v_pk_mul_f32 v[46:47], v[46:47], v[212:213]
	v_pk_mul_f32 v[48:49], v[48:49], v[214:215]
	v_pk_mul_f32 v[44:45], v[44:45], v[132:133]
	v_pk_mul_f32 v[38:39], v[38:39], v[236:237]
	v_mfma_f32_32x32x16_bf16 v[82:97], v[126:129], v[216:219], v[82:97]
	v_mul_f32_e64 v40, v40, v238
	v_mul_f32_e64 v41, v41, v239
	v_mul_f32_e64 v36, v36, v234
	v_mul_f32_e64 v37, v37, v235
	v_mul_f32_e64 v34, v34, v232
	v_mul_f32_e64 v35, v35, v233
	v_mfma_f32_32x32x16_bf16 v[66:81], v[122:125], v[216:219], v[66:81]
	ds_read_b128 v[122:125], v207 offset:64
	ds_read_b128 v[126:129], v207 offset:96
	ds_read_b128 v[130:133], v207
	ds_read_b128 v[212:215], v207 offset:32
	s_waitcnt lgkmcnt(0)
	v_pk_mul_f32 v[58:59], v[58:59], v[122:123]
	v_pk_mul_f32 v[62:63], v[62:63], v[126:127]
	v_pk_mul_f32 v[64:65], v[64:65], v[128:129]
	v_pk_mul_f32 v[54:55], v[54:55], v[212:213]
	v_pk_mul_f32 v[60:61], v[60:61], v[124:125]
	v_pk_mul_f32 v[56:57], v[56:57], v[214:215]
	v_pk_mul_f32 v[52:53], v[52:53], v[132:133]
	v_pk_mul_f32 v[50:51], v[50:51], v[130:131]
	v_mfma_f32_32x32x16_bf16 v[82:97], v[118:121], v[220:223], v[82:97]
	v_mfma_f32_32x32x16_bf16 v[66:81], v[114:117], v[220:223], v[66:81]
	ds_read_b128 v[114:117], v240 offset:24576
	ds_read_b128 v[118:121], v240 offset:28672
	ds_read_b128 v[122:125], v241 offset:24576
	ds_read_b128 v[126:129], v241 offset:28672
	ds_read_b128 v[130:133], v242 offset:24576
	ds_read_b128 v[212:215], v242 offset:28672
	ds_read_b128 v[216:219], v243 offset:24576
	ds_read_b128 v[220:223], v243 offset:28672
	v_mfma_f32_32x32x16_bf16 v[82:97], v[182:185], v[110:113], v[82:97]
	v_mfma_f32_32x32x16_bf16 v[66:81], v[186:189], v[110:113], v[66:81]
	v_mfma_f32_32x32x16_bf16 v[82:97], v[190:193], v[106:109], v[82:97]
	v_mfma_f32_32x32x16_bf16 v[66:81], v[194:197], v[106:109], v[66:81]
	v_mfma_f32_32x32x16_bf16 v[82:97], v[198:201], v[102:105], v[82:97]
	v_mfma_f32_32x32x16_bf16 v[66:81], v[208:211], v[102:105], v[66:81]
	v_mfma_f32_32x32x16_bf16 v[82:97], v[224:227], v[98:101], v[82:97]
	v_mfma_f32_32x32x16_bf16 v[66:81], v[228:231], v[98:101], v[66:81]
	s_cmp_eq_u32 s8, -1
	s_cbranch_scc1 .Lhalf_b_0
	s_cmp_lt_u32 s31, 0x400
	s_cbranch_scc1 .Lhalf_b_0
	s_add_i32 m0, s99, 0x0
	s_nop 0
	global_load_lds_dwordx4 v134, s[100:101] nt
	s_add_i32 m0, s99, 0x400
	s_nop 0
	global_load_lds_dwordx4 v245, s[100:101] nt
	s_add_i32 m0, s99, 0x800
	s_nop 0
	global_load_lds_dwordx4 v246, s[100:101] nt
	s_add_i32 m0, s99, 0xc00
	s_nop 0
	global_load_lds_dwordx4 v247, s[100:101] nt
	s_add_i32 m0, s99, 0x1000
	s_nop 0
	global_load_lds_dwordx4 v248, s[100:101] nt
	s_add_i32 m0, s65, 0xa000
	s_nop 0
	global_load_lds_dwordx4 v134, s[66:67] nt
	s_add_i32 m0, s65, 0xa400
	s_nop 0
	global_load_lds_dwordx4 v245, s[66:67] nt
	s_add_i32 m0, s65, 0xa800
	s_nop 0
	global_load_lds_dwordx4 v246, s[66:67] nt
	s_add_i32 m0, s65, 0xac00
	s_nop 0
	global_load_lds_dwordx4 v247, s[66:67] nt
.Lhalf_b_0:
	ds_read_b128 v[182:185], v240 offset:32768
	ds_read_b128 v[186:189], v240 offset:36864
	ds_read_b128 v[190:193], v241 offset:32768
	ds_read_b128 v[194:197], v241 offset:36864
	ds_read_b128 v[198:201], v242 offset:32768
	ds_read_b128 v[208:211], v242 offset:36864
	ds_read_b128 v[224:227], v243 offset:32768
	ds_read_b128 v[228:231], v243 offset:36864
	s_waitcnt lgkmcnt(0)
	v_mfma_f32_32x32x16_bf16 v[2:17], v[114:117], v[110:113], v[2:17]
	v_mfma_f32_32x32x16_bf16 v[18:33], v[118:121], v[110:113], v[18:33]
	v_mfma_f32_32x32x16_bf16 v[2:17], v[122:125], v[106:109], v[2:17]
	v_mfma_f32_32x32x16_bf16 v[18:33], v[126:129], v[106:109], v[18:33]
	v_mfma_f32_32x32x16_bf16 v[2:17], v[130:133], v[102:105], v[2:17]
	v_mfma_f32_32x32x16_bf16 v[18:33], v[212:215], v[102:105], v[18:33]
	v_mfma_f32_32x32x16_bf16 v[2:17], v[216:219], v[98:101], v[2:17]
	v_mfma_f32_32x32x16_bf16 v[18:33], v[220:223], v[98:101], v[18:33]
	s_add_i32 s64, s8, 1
	s_and_b64 s[22:23], s[10:11], exec
	s_cselect_b32 s22, s91, s64
	s_lshl_b32 s22, s22, 6
	s_add_u32 s23, s20, s22
	v_cndmask_b32_e64 v114, v82, v83, s[0:1]
	s_addc_u32 s22, s21, 0
	v_mfma_f32_32x32x16_bf16 v[34:49], v[182:185], v[110:113], v[34:49]
	v_mov_b32_dpp v114, v114 quad_perm:[1,0,3,2] row_mask:0xf bank_mask:0xf bound_ctrl:1
	v_cndmask_b32_e64 v83, v83, v114, s[0:1]
	v_cndmask_b32_e64 v82, v114, v82, s[0:1]
	v_cvt_pk_bf16_f32 v114, v82, v83
	v_readfirstlane_b32 s98, v158
	v_readfirstlane_b32 s99, v159
	v_and_b32_e32 v244, 30, v137
	v_lshlrev_b32_e32 v244, 1, v244
	v_lshl_add_u32 v244, v136, 11, v244
	s_lshl_b32 s100, s23, 11
	s_add_u32 s98, s98, s100
	s_addc_u32 s99, s99, 0
	s_add_u32 s100, s98, 0x800
	s_addc_u32 s101, s99, 0
	global_store_dword v244, v114, s[100:101] offset:-2048
	v_mov_b32_e32 v82, v84
	v_mfma_f32_32x32x16_bf16 v[50:65], v[186:189], v[110:113], v[50:65]
	v_cndmask_b32_e64 v83, v82, v85, s[0:1]
	s_add_i32 s8, s8, -1
	s_add_i32 s90, s90, 1
	v_mov_b32_dpp v83, v83 quad_perm:[1,0,3,2] row_mask:0xf bank_mask:0xf bound_ctrl:1
	v_cndmask_b32_e64 v84, v85, v83, s[0:1]
	v_cndmask_b32_e64 v82, v83, v82, s[0:1]
	v_cvt_pk_bf16_f32 v84, v82, v84
	global_store_dword v244, v84, s[100:101] offset:2048
	v_mov_b32_e32 v82, v87
	v_mfma_f32_32x32x16_bf16 v[34:49], v[190:193], v[106:109], v[34:49]
	v_cndmask_b32_e64 v83, v86, v82, s[0:1]
	s_nop 1
	v_mov_b32_dpp v83, v83 quad_perm:[1,0,3,2] row_mask:0xf bank_mask:0xf bound_ctrl:1
	v_cndmask_b32_e64 v82, v82, v83, s[0:1]
	v_cndmask_b32_e64 v83, v83, v86, s[0:1]
	v_cvt_pk_bf16_f32 v84, v83, v82
	s_add_u32 s100, s98, 0x4800
	s_addc_u32 s101, s99, 0
	global_store_dword v244, v84, s[100:101] offset:-2048
	v_mov_b32_e32 v82, v88
	v_mfma_f32_32x32x16_bf16 v[50:65], v[194:197], v[106:109], v[50:65]
; DI int crow(int r, int hi) { return (r & 3) + 8 * (r >> 2) + 4 * hi; }
; DI unsigned pkbf(float a, float b) { f32x2 v = {a, b}; bfx2 r = __builtin_convertvector(v, bfx2); return __builtin_bit_cast(unsigned, r); }
; DI void phase_gla_chain(const Params& P, int l, int task0, int ntask_stride, LAS unsigned char* lds) {
;     ...
;         __syncthreads();
;         CH_ISSUE(0, 0);
;         for (int n = 0; n < 64; ++n) {
;             const int b = n & 1;
;             if (n == 0) asm volatile("s_waitcnt vmcnt(0)" ::: "memory"); else asm volatile("s_waitcnt vmcnt(16)" ::: "memory");
;             __builtin_amdgcn_s_barrier();
;             asm volatile("" ::: "memory");
;             if (n + 1 < 64) CH_ISSUE(n + 1, b ^ 1);
;     ...
;             { const int cs = dir ? 63 - n : n; const size_t tokb = (size_t)sq * SEQL + cs * 64; const int odd = lane & 1;
;               bf16_t* ob = OFB + (size_t)dir * MTOK * 1024 + h * 256 + wid * 32 + (r32 & ~1);
; #pragma unroll
;               for (int ib = 0; ib < 2; ++ib)
; #pragma unroll
;                   for (int x = 0; x < 16; x += 2) { float ea_ = o[ib][x], eb_ = o[ib][x + 1]; asm volatile("" : "+v"(ea_), "+v"(eb_)); const float mine = odd ? eb_ : ea_, give = odd ? ea_ : eb_;
;                       const float got = __int_as_float(__builtin_amdgcn_update_dpp(0, __float_as_int(give), 0xB1, 0xF, 0xF, true));
;                       const unsigned w = odd ? pkbf(got, mine) : pkbf(mine, got);
;                       *(unsigned*)(ob + (tokb + ib * 32 + crow(x + odd, hi)) * 1024) = w; } }
	v_cndmask_b32_e64 v83, v82, v89, s[0:1]
	s_nop 1
	v_mov_b32_dpp v83, v83 quad_perm:[1,0,3,2] row_mask:0xf bank_mask:0xf bound_ctrl:1
	v_cndmask_b32_e64 v84, v89, v83, s[0:1]
	v_cndmask_b32_e64 v82, v83, v82, s[0:1]
	v_cvt_pk_bf16_f32 v84, v82, v84
	global_store_dword v244, v84, s[100:101] offset:2048
	v_mov_b32_e32 v82, v90
	v_mfma_f32_32x32x16_bf16 v[34:49], v[198:201], v[102:105], v[34:49]
	v_cndmask_b32_e64 v83, v82, v91, s[0:1]
	s_nop 1
	v_mov_b32_dpp v83, v83 quad_perm:[1,0,3,2] row_mask:0xf bank_mask:0xf bound_ctrl:1
	v_cndmask_b32_e64 v84, v91, v83, s[0:1]
	v_cndmask_b32_e64 v82, v83, v82, s[0:1]
	v_cvt_pk_bf16_f32 v84, v82, v84
	s_add_u32 s100, s98, 0x8800
	s_addc_u32 s101, s99, 0
	global_store_dword v244, v84, s[100:101] offset:-2048
	v_mov_b32_e32 v82, v93
	v_mfma_f32_32x32x16_bf16 v[50:65], v[208:211], v[102:105], v[50:65]
	v_cndmask_b32_e64 v83, v92, v82, s[0:1]
	s_nop 1
	v_mov_b32_dpp v83, v83 quad_perm:[1,0,3,2] row_mask:0xf bank_mask:0xf bound_ctrl:1
	v_cndmask_b32_e64 v82, v82, v83, s[0:1]
	v_cndmask_b32_e64 v83, v83, v92, s[0:1]
	v_cvt_pk_bf16_f32 v84, v83, v82
	global_store_dword v244, v84, s[100:101] offset:2048
	v_mov_b32_e32 v82, v94
	v_mfma_f32_32x32x16_bf16 v[34:49], v[224:227], v[98:101], v[34:49]
	v_cndmask_b32_e64 v83, v82, v95, s[0:1]
	s_nop 1
	v_mov_b32_dpp v83, v83 quad_perm:[1,0,3,2] row_mask:0xf bank_mask:0xf bound_ctrl:1
	v_cndmask_b32_e64 v84, v95, v83, s[0:1]
	v_cndmask_b32_e64 v82, v83, v82, s[0:1]
	v_cvt_pk_bf16_f32 v84, v82, v84
	s_add_u32 s100, s98, 0xc800
	s_addc_u32 s101, s99, 0
	global_store_dword v244, v84, s[100:101] offset:-2048
	v_mov_b32_e32 v82, v96
	v_mfma_f32_32x32x16_bf16 v[50:65], v[228:231], v[98:101], v[50:65]
	v_cndmask_b32_e64 v83, v82, v97, s[0:1]
	s_nop 1
	v_mov_b32_dpp v83, v83 quad_perm:[1,0,3,2] row_mask:0xf bank_mask:0xf bound_ctrl:1
	v_cndmask_b32_e64 v84, v97, v83, s[0:1]
	v_cndmask_b32_e64 v82, v83, v82, s[0:1]
	v_cvt_pk_bf16_f32 v84, v82, v84
	global_store_dword v244, v84, s[100:101] offset:2048
	s_or_b32 s23, s23, 32
	v_cndmask_b32_e64 v82, v66, v67, s[0:1]
	s_nop 0
	v_mov_b32_dpp v82, v82 quad_perm:[1,0,3,2] row_mask:0xf bank_mask:0xf bound_ctrl:1
	v_cndmask_b32_e64 v67, v67, v82, s[0:1]
	v_cndmask_b32_e64 v66, v82, v66, s[0:1]
	v_cvt_pk_bf16_f32 v82, v66, v67
	s_add_u32 s100, s98, 0x10800
	s_addc_u32 s101, s99, 0
	global_store_dword v244, v82, s[100:101] offset:-2048
	v_mov_b32_e32 v66, v68
	s_nop 0
	v_cndmask_b32_e64 v67, v66, v69, s[0:1]
	s_nop 1
	v_mov_b32_dpp v67, v67 quad_perm:[1,0,3,2] row_mask:0xf bank_mask:0xf bound_ctrl:1
	v_cndmask_b32_e64 v68, v69, v67, s[0:1]
	v_cndmask_b32_e64 v66, v67, v66, s[0:1]
	v_cvt_pk_bf16_f32 v68, v66, v68
	global_store_dword v244, v68, s[100:101] offset:2048
	v_mov_b32_e32 v66, v70
	s_nop 0
	v_cndmask_b32_e64 v67, v66, v71, s[0:1]
	s_nop 1
	v_mov_b32_dpp v67, v67 quad_perm:[1,0,3,2] row_mask:0xf bank_mask:0xf bound_ctrl:1
	v_cndmask_b32_e64 v68, v71, v67, s[0:1]
	v_cndmask_b32_e64 v66, v67, v66, s[0:1]
	v_cvt_pk_bf16_f32 v68, v66, v68
	s_add_u32 s100, s98, 0x14800
	s_addc_u32 s101, s99, 0
	global_store_dword v244, v68, s[100:101] offset:-2048
	v_mov_b32_e32 v66, v73
	s_nop 0
	v_cndmask_b32_e64 v67, v72, v66, s[0:1]
	s_nop 1
	v_mov_b32_dpp v67, v67 quad_perm:[1,0,3,2] row_mask:0xf bank_mask:0xf bound_ctrl:1
	v_cndmask_b32_e64 v66, v66, v67, s[0:1]
	v_cndmask_b32_e64 v67, v67, v72, s[0:1]
	v_cvt_pk_bf16_f32 v68, v67, v66
	global_store_dword v244, v68, s[100:101] offset:2048
	v_mov_b32_e32 v66, v74
	s_nop 0
	v_cndmask_b32_e64 v67, v66, v75, s[0:1]
	s_nop 1
	v_mov_b32_dpp v67, v67 quad_perm:[1,0,3,2] row_mask:0xf bank_mask:0xf bound_ctrl:1
	v_cndmask_b32_e64 v68, v75, v67, s[0:1]
	v_cndmask_b32_e64 v66, v67, v66, s[0:1]
	v_cvt_pk_bf16_f32 v68, v66, v68
	s_add_u32 s100, s98, 0x18800
	s_addc_u32 s101, s99, 0
	global_store_dword v244, v68, s[100:101] offset:-2048
	v_mov_b32_e32 v66, v76
	s_nop 0
	v_cndmask_b32_e64 v67, v66, v77, s[0:1]
	s_nop 1
	v_mov_b32_dpp v67, v67 quad_perm:[1,0,3,2] row_mask:0xf bank_mask:0xf bound_ctrl:1
	v_cndmask_b32_e64 v68, v77, v67, s[0:1]
	v_cndmask_b32_e64 v66, v67, v66, s[0:1]
	v_cvt_pk_bf16_f32 v68, v66, v68
	global_store_dword v244, v68, s[100:101] offset:2048
	v_mov_b32_e32 v66, v79
	s_nop 0
	v_cndmask_b32_e64 v67, v78, v66, s[0:1]
	s_nop 1
	v_mov_b32_dpp v67, v67 quad_perm:[1,0,3,2] row_mask:0xf bank_mask:0xf bound_ctrl:1
	v_cndmask_b32_e64 v66, v66, v67, s[0:1]
	v_cndmask_b32_e64 v67, v67, v78, s[0:1]
	v_cvt_pk_bf16_f32 v68, v67, v66
	s_add_u32 s100, s98, 0x1c800
	s_addc_u32 s101, s99, 0
	global_store_dword v244, v68, s[100:101] offset:-2048
	v_mov_b32_e32 v66, v81
	s_nop 0
	v_cndmask_b32_e64 v67, v80, v66, s[0:1]
	s_nop 1
	v_mov_b32_dpp v67, v67 quad_perm:[1,0,3,2] row_mask:0xf bank_mask:0xf bound_ctrl:1
	v_cndmask_b32_e64 v66, v66, v67, s[0:1]
	v_cndmask_b32_e64 v67, v67, v80, s[0:1]
	v_cvt_pk_bf16_f32 v68, v67, v66
	global_store_dword v244, v68, s[100:101] offset:2048
	s_cmp_eq_u32 s8, -2
	s_cbranch_scc1 .LBB0_403
.LBB0_410:
	s_add_i32 s91, s90, -1
	s_waitcnt vmcnt(16)
	s_barrier
	s_and_b32 s92, s91, 1
	s_cmp_eq_u32 s8, -1
	s_cbranch_scc1 .LBB0_409
	s_and_b64 s[22:23], s[10:11], exec
	s_cselect_b32 s22, s90, s8
	s_add_i32 s22, s22, s89
	s_lshl_b32 s22, s22, 2
	s_or_b32 s96, s22, s88
	s_ashr_i32 s97, s96, 31
	s_add_u32 s22, s25, s96
	s_addc_u32 s23, 0, s97
	s_mul_i32 s93, s23, 0xa000
	s_mul_hi_u32 vcc_lo, s22, 0xa000
	s_add_i32 vcc_lo, vcc_lo, s93
	s_mul_i32 s93, s22, 0xa000
	s_add_u32 vcc_hi, s27, s93
	s_addc_u32 vcc_lo, s28, vcc_lo
	s_lshl_b64 s[96:97], s[96:97], 15
	s_add_u32 s68, s29, s96
	s_addc_u32 s69, s30, s97
	s_xor_b32 s93, s92, 1
	s_mul_i32 s93, s93, 0x12400
	s_add_i32 s93, s93, 0
	v_add_u32_e32 v245, 0x400, v134
	v_add_u32_e32 v246, 0x800, v134
	v_add_u32_e32 v247, 0xc00, v134
	v_add_u32_e32 v248, 0x1000, v134
	s_lshl_b32 s32, s31, 4
	s_lshl_b32 s98, s31, 2
	s_add_i32 s98, s98, s32
	s_add_u32 s100, vcc_hi, s98
	s_addc_u32 s101, vcc_lo, 0
	s_add_i32 s99, s93, s98
	s_add_u32 s66, s68, s32
	s_addc_u32 s67, s69, 0
	s_add_i32 s65, s93, s32
	s_cmp_ge_u32 s31, 0x400
	s_cbranch_scc1 .Lhalf_t_0
	s_add_i32 m0, s99, 0x0
	s_nop 0
	global_load_lds_dwordx4 v134, s[100:101] nt
	s_add_i32 m0, s99, 0x400
	s_nop 0
	global_load_lds_dwordx4 v245, s[100:101] nt
	s_add_i32 m0, s99, 0x800
	s_nop 0
	global_load_lds_dwordx4 v246, s[100:101] nt
	s_add_i32 m0, s99, 0xc00
	s_nop 0
	global_load_lds_dwordx4 v247, s[100:101] nt
	s_add_i32 m0, s99, 0x1000
	s_nop 0
	global_load_lds_dwordx4 v248, s[100:101] nt
	s_add_i32 m0, s65, 0xa000
	s_nop 0
	global_load_lds_dwordx4 v134, s[66:67] nt
	s_add_i32 m0, s65, 0xa400
	s_nop 0
	global_load_lds_dwordx4 v245, s[66:67] nt
	s_add_i32 m0, s65, 0xa800
	s_nop 0
	global_load_lds_dwordx4 v246, s[66:67] nt
	s_add_i32 m0, s65, 0xac00
	s_nop 0
	global_load_lds_dwordx4 v247, s[66:67] nt
.Lhalf_t_0:
	s_and_b64 vcc, exec, s[2:3]
	s_cbranch_vccnz .LBB0_409
	s_add_i32 s64, s93, s31
	s_lshl_b64 s[22:23], s[22:23], 9
	s_add_i32 m0, s64, 0x12000
	v_lshl_add_u64 v[66:67], v[156:157], 0, s[22:23]
	global_load_lds_dword v[66:67], off
	s_branch .LBB0_409

; #define LAS __attribute__((address_space(3)))
; #define RD_QD(dst, s0) _Pragma("unroll") for (int s_ = 0; s_ < 4; ++s_) { dst[s_] = *(const LAS bf16x8*)(B + CH_QD + i0 * 256 + (((2 * ((s0) + s_) + hi) ^ (i0 & 15)) << 4)); \
;                 dst[4 + s_] = *(const LAS bf16x8*)(B + CH_QD + i1 * 256 + (((2 * ((s0) + s_) + hi) ^ (i1 & 15)) << 4)); }
; #define DECAY(db_) do { f32x4 dc_[4]; _Pragma("unroll") for (int a4_ = 0; a4_ < 4; ++a4_) dc_[a4_] = *(const LAS f32x4*)(B + CH_DEC + ((db_) * 32 + 8 * a4_ + 4 * hi) * 4); \
;                 _Pragma("unroll") for (int a4_ = 0; a4_ < 4; ++a4_) _Pragma("unroll") for (int b4_ = 0; b4_ < 4; ++b4_) T[db_][a4_ * 4 + b4_] *= dc_[a4_][b4_]; } while (0)
; DI void phase_gla_chain(const Params& P, int l, int task0, int ntask_stride, LAS unsigned char* lds) {
;     ...
;             const int i0 = r32, i1 = 32 + r32; const int vv = wid * 32 + r32;
;             bf16x8 fa[8], fb[8], vf[4];
;             f32x16 o[2]; for (int x = 0; x < 16; ++x) { o[0][x] = 0.f; o[1][x] = 0.f; }
;     ...
;             RD_QD(fa, 0);
; #pragma unroll
;             for (int ks = 0; ks < 4; ++ks) vf[ks] = *(const LAS bf16x8*)(B + CH_VT + vv * 128 + (((2 * ks + hi) ^ ((vv >> 1) & 7)) << 4));
;             __builtin_amdgcn_sched_barrier(0);
;             RD_QD(fb, 4);
;             __builtin_amdgcn_sched_barrier(0);
;             MM_QD(fa, 0);
;             DECAY(0); DECAY(1);
;             __builtin_amdgcn_sched_barrier(0);
; #pragma unroll
;             for (int ks = 0; ks < 4; ++ks) { fa[ks] = *(const LAS bf16x8*)(B + CH_AM + i0 * 128 + (((2 * ks + hi) ^ ((i0 >> 1) & 7)) << 4)); fa[4 + ks] = *(const LAS bf16x8*)(B + CH_AM + i1 * 128 + (((2 * ks + hi) ^ ((i1 >> 1) & 7)) << 4)); }
;             __builtin_amdgcn_sched_barrier(0);
;             MM_QD(fb, 4);
;             DECAY(2); DECAY(3);
;             __builtin_amdgcn_sched_barrier(0);
.LBB0_971:
	s_mul_i32 s84, s84, 0x12400
	s_add_i32 s22, s84, 0
	v_add_u32_e32 v74, s22, v201
	v_add_u32_e32 v75, s22, v141
	v_add_u32_e32 v66, v74, v149
	v_add_u32_e32 v70, v75, v149
	v_add_u32_e32 v76, v74, v151
	ds_read_b128 v[66:69], v66
	ds_read_b128 v[70:73], v70
	v_add_u32_e32 v77, v75, v151
	ds_read_b128 v[182:185], v76
	ds_read_b128 v[186:189], v77
	v_add_u32_e32 v76, v74, v153
	v_add_u32_e32 v77, v75, v153
	ds_read_b128 v[190:193], v76
	ds_read_b128 v[194:197], v77
	v_add_u32_e32 v76, v74, v160
	v_add_u32_e32 v77, v75, v160
	ds_read_b128 v[204:207], v76
	ds_read_b128 v[208:211], v77
	v_add_u32_e32 v76, s22, v173
	v_add_u32_e32 v77, v76, v162
	v_add_u32_e32 v78, v76, v164
	ds_read_b128 v[110:113], v77 offset:40960
	ds_read_b128 v[106:109], v78 offset:40960
	v_add_u32_e32 v77, v76, v165
	v_add_u32_e32 v76, v76, v166
	ds_read_b128 v[102:105], v77 offset:40960
	ds_read_b128 v[98:101], v76 offset:40960
	v_add_u32_e32 v76, v74, v167
	v_add_u32_e32 v77, v75, v167
	ds_read_b128 v[212:215], v76
	ds_read_b128 v[216:219], v77
	v_add_u32_e32 v76, v74, v168
	v_add_u32_e32 v77, v75, v168
	ds_read_b128 v[220:223], v76
	ds_read_b128 v[130:133], v77
	v_add_u32_e32 v76, v74, v169
	v_add_u32_e32 v74, v74, v170
	v_add_u32_e32 v77, v75, v169
	ds_read_b128 v[126:129], v76
	ds_read_b128 v[122:125], v77
	v_add_u32_e32 v75, v75, v170
	ds_read_b128 v[118:121], v74
	ds_read_b128 v[114:117], v75
	v_cvt_pk_bf16_f32 v74, v2, v3
	v_cvt_pk_bf16_f32 v75, v4, v5
	v_cvt_pk_bf16_f32 v76, v6, v7
	v_cvt_pk_bf16_f32 v77, v8, v9
	v_cvt_pk_bf16_f32 v224, v10, v11
	v_cvt_pk_bf16_f32 v225, v12, v13
	s_waitcnt lgkmcnt(0)
	v_mfma_f32_32x32x16_bf16 v[82:97], v[66:69], v[74:77], 0
	v_cvt_pk_bf16_f32 v226, v14, v15
	v_cvt_pk_bf16_f32 v227, v16, v17
	v_add_u32_e32 v198, s22, v146
	v_add_u32_e32 v199, 0x12000, v198
	v_cvt_pk_bf16_f32 v228, v26, v27
	v_cvt_pk_bf16_f32 v229, v28, v29
	v_cvt_pk_bf16_f32 v230, v30, v31
	v_mfma_f32_32x32x16_bf16 v[66:81], v[70:73], v[74:77], 0
	v_cvt_pk_bf16_f32 v231, v32, v33
	v_mfma_f32_32x32x16_bf16 v[82:97], v[182:185], v[224:227], v[82:97]
	v_cvt_pk_bf16_f32 v182, v18, v19
	v_cvt_pk_bf16_f32 v183, v20, v21
	v_cvt_pk_bf16_f32 v184, v22, v23
	v_cvt_pk_bf16_f32 v185, v24, v25
	v_mfma_f32_32x32x16_bf16 v[66:81], v[186:189], v[224:227], v[66:81]
	ds_read_b128 v[186:189], v199 offset:64
	ds_read_b128 v[224:227], v199 offset:96
	ds_read_b128 v[232:235], v199
	ds_read_b128 v[236:239], v199 offset:32
	s_waitcnt lgkmcnt(0)
	v_pk_mul_f32 v[10:11], v[10:11], v[186:187]
	v_pk_mul_f32 v[12:13], v[12:13], v[188:189]
	v_pk_mul_f32 v[14:15], v[14:15], v[224:225]
	v_pk_mul_f32 v[6:7], v[6:7], v[236:237]
	v_pk_mul_f32 v[16:17], v[16:17], v[226:227]
	v_mfma_f32_32x32x16_bf16 v[82:97], v[190:193], v[182:185], v[82:97]
	v_mul_f32_e64 v8, v8, v238
	v_mul_f32_e64 v9, v9, v239
	v_mul_f32_e64 v4, v4, v234
	v_mul_f32_e64 v5, v5, v235
	v_mul_f32_e64 v2, v2, v232
	v_mul_f32_e64 v3, v3, v233
	v_mfma_f32_32x32x16_bf16 v[66:81], v[194:197], v[182:185], v[66:81]
	v_add_u32_e32 v194, 0x12080, v198
	ds_read_b128 v[182:185], v194 offset:64
	ds_read_b128 v[186:189], v194 offset:96
	ds_read_b128 v[190:193], v194
	ds_read_b128 v[194:197], v194 offset:32
	s_waitcnt lgkmcnt(0)
	v_pk_mul_f32 v[26:27], v[26:27], v[182:183]
	v_pk_mul_f32 v[30:31], v[30:31], v[186:187]
	v_pk_mul_f32 v[32:33], v[32:33], v[188:189]
	v_pk_mul_f32 v[22:23], v[22:23], v[194:195]
	v_pk_mul_f32 v[28:29], v[28:29], v[184:185]
	v_pk_mul_f32 v[24:25], v[24:25], v[196:197]
	v_pk_mul_f32 v[20:21], v[20:21], v[192:193]
	v_pk_mul_f32 v[18:19], v[18:19], v[190:191]
	v_mfma_f32_32x32x16_bf16 v[82:97], v[204:207], v[228:231], v[82:97]
	v_mfma_f32_32x32x16_bf16 v[66:81], v[208:211], v[228:231], v[66:81]
	v_add_u32_e32 v199, s22, v143
	v_add_u32_e32 v224, s22, v145
	v_add_u32_e32 v240, v199, v162
	v_add_u32_e32 v186, v224, v162
	v_add_u32_e32 v241, v199, v164
	v_add_u32_e32 v194, v224, v164
	v_add_u32_e32 v242, v199, v165
	v_add_u32_e32 v208, v224, v165
	v_add_u32_e32 v199, v199, v166
	v_add_u32_e32 v228, v224, v166
	ds_read_b128 v[182:185], v240 offset:16384
	ds_read_b128 v[186:189], v186 offset:16384
	ds_read_b128 v[190:193], v241 offset:16384
	ds_read_b128 v[194:197], v194 offset:16384
	ds_read_b128 v[204:207], v242 offset:16384
	ds_read_b128 v[208:211], v208 offset:16384
	ds_read_b128 v[224:227], v199 offset:16384
	ds_read_b128 v[228:231], v228 offset:16384
	v_cvt_pk_bf16_f32 v232, v34, v35
	v_cvt_pk_bf16_f32 v233, v36, v37
	v_cvt_pk_bf16_f32 v234, v38, v39
	v_cvt_pk_bf16_f32 v235, v40, v41
	s_nop 1
	v_mfma_f32_32x32x16_bf16 v[82:97], v[212:215], v[232:235], v[82:97]
	v_cvt_pk_bf16_f32 v212, v42, v43
	v_cvt_pk_bf16_f32 v213, v44, v45
	v_cvt_pk_bf16_f32 v214, v46, v47
	v_cvt_pk_bf16_f32 v215, v48, v49
	v_mfma_f32_32x32x16_bf16 v[66:81], v[216:219], v[232:235], v[66:81]
	v_cvt_pk_bf16_f32 v216, v50, v51
	v_cvt_pk_bf16_f32 v217, v52, v53
	v_cvt_pk_bf16_f32 v218, v54, v55
	v_cvt_pk_bf16_f32 v219, v56, v57
	v_mfma_f32_32x32x16_bf16 v[82:97], v[220:223], v[212:215], v[82:97]
	v_add_u32_e32 v223, 0x12100, v198
	v_add_u32_e32 v198, 0x12180, v198
	v_cvt_pk_bf16_f32 v220, v58, v59
	v_cvt_pk_bf16_f32 v221, v60, v61
	v_cvt_pk_bf16_f32 v222, v62, v63
	v_mfma_f32_32x32x16_bf16 v[66:81], v[130:133], v[212:215], v[66:81]
	ds_read_b128 v[130:133], v223 offset:64
	ds_read_b128 v[212:215], v223 offset:96
	ds_read_b128 v[232:235], v223
	ds_read_b128 v[236:239], v223 offset:32
	v_cvt_pk_bf16_f32 v223, v64, v65
	s_waitcnt lgkmcnt(0)
; #define LAS __attribute__((address_space(3)))
; DI int crow(int r, int hi) { return (r & 3) + 8 * (r >> 2) + 4 * hi; }
; DI unsigned pkbf(float a, float b) { f32x2 v = {a, b}; bfx2 r = __builtin_convertvector(v, bfx2); return __builtin_bit_cast(unsigned, r); }
; #define MM_KT(src, db0) _Pragma("unroll") for (int q_ = 0; q_ < 2; ++q_) { \
;                 _Pragma("unroll") for (int ks_ = 0; ks_ < 4; ++ks_) T[(db0) + q_] = __builtin_amdgcn_mfma_f32_32x32x16_bf16(src[q_ * 4 + ks_], vf[ks_], T[(db0) + q_], 0, 0, 0); }
; DI void phase_gla_chain(const Params& P, int l, int task0, int ntask_stride, LAS unsigned char* lds) {
;     ...
;             for (int ks = 0; ks < 4; ++ks) { fa[ks] = *(const LAS bf16x8*)(B + CH_AM + i0 * 128 + (((2 * ks + hi) ^ ((i0 >> 1) & 7)) << 4)); fa[4 + ks] = *(const LAS bf16x8*)(B + CH_AM + i1 * 128 + (((2 * ks + hi) ^ ((i1 >> 1) & 7)) << 4)); }
;             __builtin_amdgcn_sched_barrier(0);
;             MM_QD(fb, 4);
;             DECAY(2); DECAY(3);
;             __builtin_amdgcn_sched_barrier(0);
;             RD_KT(fb, 0);
;             __builtin_amdgcn_sched_barrier(0);
; #pragma unroll
;             for (int ks = 0; ks < 4; ++ks) { o[0] = __builtin_amdgcn_mfma_f32_32x32x16_bf16(fa[ks], vf[ks], o[0], 0, 0, 0); o[1] = __builtin_amdgcn_mfma_f32_32x32x16_bf16(fa[4 + ks], vf[ks], o[1], 0, 0, 0); }
;             __builtin_amdgcn_sched_barrier(0);
;             RD_KT(fa, 2);
;             __builtin_amdgcn_sched_barrier(0);
;             MM_KT(fb, 0);
;             __builtin_amdgcn_sched_barrier(0);
;             MM_KT(fa, 2);
;     ...
;             { const int cs = dir ? 63 - n : n; const size_t tokb = (size_t)sq * SEQL + cs * 64; const int odd = lane & 1;
;               bf16_t* ob = OFB + (size_t)dir * MTOK * 1024 + h * 256 + wid * 32 + (r32 & ~1);
; #pragma unroll
;               for (int ib = 0; ib < 2; ++ib)
; #pragma unroll
;                   for (int x = 0; x < 16; x += 2) { float ea_ = o[ib][x], eb_ = o[ib][x + 1]; asm volatile("" : "+v"(ea_), "+v"(eb_)); const float mine = odd ? eb_ : ea_, give = odd ? ea_ : eb_;
;                       const float got = __int_as_float(__builtin_amdgcn_update_dpp(0, __float_as_int(give), 0xB1, 0xF, 0xF, true));
;                       const unsigned w = odd ? pkbf(got, mine) : pkbf(mine, got);
;                       *(unsigned*)(ob + (tokb + ib * 32 + crow(x + odd, hi)) * 1024) = w; } }
	v_pk_mul_f32 v[42:43], v[42:43], v[130:131]
	v_pk_mul_f32 v[46:47], v[46:47], v[212:213]
	v_pk_mul_f32 v[48:49], v[48:49], v[214:215]
	v_pk_mul_f32 v[44:45], v[44:45], v[132:133]
	v_pk_mul_f32 v[38:39], v[38:39], v[236:237]
	v_mfma_f32_32x32x16_bf16 v[82:97], v[126:129], v[216:219], v[82:97]
	v_mul_f32_e64 v40, v40, v238
	v_mul_f32_e64 v41, v41, v239
	v_mul_f32_e64 v36, v36, v234
	v_mul_f32_e64 v37, v37, v235
	v_mul_f32_e64 v34, v34, v232
	v_mul_f32_e64 v35, v35, v233
	v_mfma_f32_32x32x16_bf16 v[66:81], v[122:125], v[216:219], v[66:81]
	ds_read_b128 v[122:125], v198 offset:64
	ds_read_b128 v[126:129], v198 offset:96
	ds_read_b128 v[130:133], v198
	ds_read_b128 v[212:215], v198 offset:32
	s_waitcnt lgkmcnt(0)
	v_pk_mul_f32 v[58:59], v[58:59], v[122:123]
	v_pk_mul_f32 v[62:63], v[62:63], v[126:127]
	v_pk_mul_f32 v[64:65], v[64:65], v[128:129]
	v_pk_mul_f32 v[54:55], v[54:55], v[212:213]
	v_pk_mul_f32 v[60:61], v[60:61], v[124:125]
	v_pk_mul_f32 v[56:57], v[56:57], v[214:215]
	v_pk_mul_f32 v[52:53], v[52:53], v[132:133]
	v_pk_mul_f32 v[50:51], v[50:51], v[130:131]
	v_mfma_f32_32x32x16_bf16 v[82:97], v[118:121], v[220:223], v[82:97]
	v_mfma_f32_32x32x16_bf16 v[66:81], v[114:117], v[220:223], v[66:81]
	ds_read_b128 v[114:117], v240 offset:24576
	ds_read_b128 v[118:121], v240 offset:28672
	ds_read_b128 v[122:125], v241 offset:24576
	ds_read_b128 v[126:129], v241 offset:28672
	ds_read_b128 v[130:133], v242 offset:24576
	ds_read_b128 v[212:215], v242 offset:28672
	ds_read_b128 v[216:219], v199 offset:24576
	ds_read_b128 v[220:223], v199 offset:28672
	v_mfma_f32_32x32x16_bf16 v[82:97], v[182:185], v[110:113], v[82:97]
	v_mfma_f32_32x32x16_bf16 v[66:81], v[186:189], v[110:113], v[66:81]
	v_mfma_f32_32x32x16_bf16 v[82:97], v[190:193], v[106:109], v[82:97]
	v_mfma_f32_32x32x16_bf16 v[66:81], v[194:197], v[106:109], v[66:81]
	v_mfma_f32_32x32x16_bf16 v[82:97], v[204:207], v[102:105], v[82:97]
	v_mfma_f32_32x32x16_bf16 v[66:81], v[208:211], v[102:105], v[66:81]
	v_mfma_f32_32x32x16_bf16 v[82:97], v[224:227], v[98:101], v[82:97]
	v_mfma_f32_32x32x16_bf16 v[66:81], v[228:231], v[98:101], v[66:81]
	s_cmp_eq_u32 s8, -1
	s_cbranch_scc1 .Lhalf_b_1
	s_cmp_lt_u32 s31, 0x400
	s_cbranch_scc1 .Lhalf_b_1
	s_add_i32 m0, s99, 0x0
	s_nop 0
	global_load_lds_dwordx4 v134, s[100:101] nt
	s_add_i32 m0, s99, 0x400
	s_nop 0
	global_load_lds_dwordx4 v245, s[100:101] nt
	s_add_i32 m0, s99, 0x800
	s_nop 0
	global_load_lds_dwordx4 v246, s[100:101] nt
	s_add_i32 m0, s99, 0xc00
	s_nop 0
	global_load_lds_dwordx4 v247, s[100:101] nt
	s_add_i32 m0, s99, 0x1000
	s_nop 0
	global_load_lds_dwordx4 v248, s[100:101] nt
	s_add_i32 m0, s90, 0xa000
	s_nop 0
	global_load_lds_dwordx4 v134, s[88:89] nt
	s_add_i32 m0, s90, 0xa400
	s_nop 0
	global_load_lds_dwordx4 v245, s[88:89] nt
	s_add_i32 m0, s90, 0xa800
	s_nop 0
	global_load_lds_dwordx4 v246, s[88:89] nt
	s_add_i32 m0, s90, 0xac00
	s_nop 0
	global_load_lds_dwordx4 v247, s[88:89] nt
.Lhalf_b_1:
	ds_read_b128 v[182:185], v240 offset:32768
	ds_read_b128 v[186:189], v240 offset:36864
	ds_read_b128 v[190:193], v241 offset:32768
	ds_read_b128 v[194:197], v241 offset:36864
	ds_read_b128 v[204:207], v242 offset:32768
	ds_read_b128 v[208:211], v242 offset:36864
	ds_read_b128 v[224:227], v199 offset:32768
	ds_read_b128 v[228:231], v199 offset:36864
	s_waitcnt lgkmcnt(0)
	v_mfma_f32_32x32x16_bf16 v[2:17], v[114:117], v[110:113], v[2:17]
	v_mfma_f32_32x32x16_bf16 v[18:33], v[118:121], v[110:113], v[18:33]
	v_mfma_f32_32x32x16_bf16 v[2:17], v[122:125], v[106:109], v[2:17]
	v_mfma_f32_32x32x16_bf16 v[18:33], v[126:129], v[106:109], v[18:33]
	v_mfma_f32_32x32x16_bf16 v[2:17], v[130:133], v[102:105], v[2:17]
	v_mfma_f32_32x32x16_bf16 v[18:33], v[212:215], v[102:105], v[18:33]
	v_mfma_f32_32x32x16_bf16 v[2:17], v[216:219], v[98:101], v[2:17]
	v_mfma_f32_32x32x16_bf16 v[18:33], v[220:223], v[98:101], v[18:33]
	s_add_i32 s64, s8, 1
	s_and_b64 s[22:23], s[10:11], exec
	s_cselect_b32 s22, s83, s64
	s_lshl_b32 s22, s22, 6
	s_add_u32 s23, s20, s22
	v_cndmask_b32_e64 v114, v82, v83, s[0:1]
	s_addc_u32 s22, s21, 0
	v_mfma_f32_32x32x16_bf16 v[34:49], v[182:185], v[110:113], v[34:49]
	v_mov_b32_dpp v114, v114 quad_perm:[1,0,3,2] row_mask:0xf bank_mask:0xf bound_ctrl:1
	v_cndmask_b32_e64 v83, v83, v114, s[0:1]
	v_cndmask_b32_e64 v82, v114, v82, s[0:1]
	v_cvt_pk_bf16_f32 v114, v82, v83
	v_readfirstlane_b32 s98, v158
	v_readfirstlane_b32 s99, v159
	v_and_b32_e32 v244, 30, v137
	v_lshlrev_b32_e32 v244, 1, v244
	v_lshl_add_u32 v244, v136, 11, v244
	s_lshl_b32 s100, s23, 11
	s_add_u32 s98, s98, s100
	s_addc_u32 s99, s99, 0
	s_add_u32 s100, s98, 0x800
	s_addc_u32 s101, s99, 0
	global_store_dword v244, v114, s[100:101] offset:-2048
	v_mov_b32_e32 v82, v84
	v_mfma_f32_32x32x16_bf16 v[50:65], v[186:189], v[110:113], v[50:65]
	v_cndmask_b32_e64 v83, v82, v85, s[0:1]
	s_add_i32 s8, s8, -1
	s_add_i32 s82, s82, 1
	v_mov_b32_dpp v83, v83 quad_perm:[1,0,3,2] row_mask:0xf bank_mask:0xf bound_ctrl:1
	v_cndmask_b32_e64 v84, v85, v83, s[0:1]
	v_cndmask_b32_e64 v82, v83, v82, s[0:1]
	v_cvt_pk_bf16_f32 v84, v82, v84
	global_store_dword v244, v84, s[100:101] offset:2048
	v_mov_b32_e32 v82, v86
	v_mfma_f32_32x32x16_bf16 v[34:49], v[190:193], v[106:109], v[34:49]
	v_cndmask_b32_e64 v83, v82, v87, s[0:1]
	s_nop 1
	v_mov_b32_dpp v83, v83 quad_perm:[1,0,3,2] row_mask:0xf bank_mask:0xf bound_ctrl:1
	v_cndmask_b32_e64 v84, v87, v83, s[0:1]
	v_cndmask_b32_e64 v82, v83, v82, s[0:1]
	v_cvt_pk_bf16_f32 v84, v82, v84
	s_add_u32 s100, s98, 0x4800
	s_addc_u32 s101, s99, 0
	global_store_dword v244, v84, s[100:101] offset:-2048
	v_mov_b32_e32 v82, v89
	v_mfma_f32_32x32x16_bf16 v[50:65], v[194:197], v[106:109], v[50:65]
; DI int crow(int r, int hi) { return (r & 3) + 8 * (r >> 2) + 4 * hi; }
; DI unsigned pkbf(float a, float b) { f32x2 v = {a, b}; bfx2 r = __builtin_convertvector(v, bfx2); return __builtin_bit_cast(unsigned, r); }
; DI void phase_gla_chain(const Params& P, int l, int task0, int ntask_stride, LAS unsigned char* lds) {
;     ...
;         __syncthreads();
;         CH_ISSUE(0, 0);
;         for (int n = 0; n < 64; ++n) {
;             const int b = n & 1;
;             if (n == 0) asm volatile("s_waitcnt vmcnt(0)" ::: "memory"); else asm volatile("s_waitcnt vmcnt(16)" ::: "memory");
;             __builtin_amdgcn_s_barrier();
;             asm volatile("" ::: "memory");
;             if (n + 1 < 64) CH_ISSUE(n + 1, b ^ 1);
;     ...
;             { const int cs = dir ? 63 - n : n; const size_t tokb = (size_t)sq * SEQL + cs * 64; const int odd = lane & 1;
;               bf16_t* ob = OFB + (size_t)dir * MTOK * 1024 + h * 256 + wid * 32 + (r32 & ~1);
; #pragma unroll
;               for (int ib = 0; ib < 2; ++ib)
; #pragma unroll
;                   for (int x = 0; x < 16; x += 2) { float ea_ = o[ib][x], eb_ = o[ib][x + 1]; asm volatile("" : "+v"(ea_), "+v"(eb_)); const float mine = odd ? eb_ : ea_, give = odd ? ea_ : eb_;
;                       const float got = __int_as_float(__builtin_amdgcn_update_dpp(0, __float_as_int(give), 0xB1, 0xF, 0xF, true));
;                       const unsigned w = odd ? pkbf(got, mine) : pkbf(mine, got);
;                       *(unsigned*)(ob + (tokb + ib * 32 + crow(x + odd, hi)) * 1024) = w; } }
	v_cndmask_b32_e64 v83, v88, v82, s[0:1]
	s_nop 1
	v_mov_b32_dpp v83, v83 quad_perm:[1,0,3,2] row_mask:0xf bank_mask:0xf bound_ctrl:1
	v_cndmask_b32_e64 v82, v82, v83, s[0:1]
	v_cndmask_b32_e64 v83, v83, v88, s[0:1]
	v_cvt_pk_bf16_f32 v84, v83, v82
	global_store_dword v244, v84, s[100:101] offset:2048
	v_mov_b32_e32 v82, v90
	v_mfma_f32_32x32x16_bf16 v[34:49], v[204:207], v[102:105], v[34:49]
	v_cndmask_b32_e64 v83, v82, v91, s[0:1]
	s_nop 1
	v_mov_b32_dpp v83, v83 quad_perm:[1,0,3,2] row_mask:0xf bank_mask:0xf bound_ctrl:1
	v_cndmask_b32_e64 v84, v91, v83, s[0:1]
	v_cndmask_b32_e64 v82, v83, v82, s[0:1]
	v_cvt_pk_bf16_f32 v84, v82, v84
	s_add_u32 s100, s98, 0x8800
	s_addc_u32 s101, s99, 0
	global_store_dword v244, v84, s[100:101] offset:-2048
	v_mov_b32_e32 v82, v92
	v_mfma_f32_32x32x16_bf16 v[50:65], v[208:211], v[102:105], v[50:65]
	v_cndmask_b32_e64 v83, v82, v93, s[0:1]
	s_nop 1
	v_mov_b32_dpp v83, v83 quad_perm:[1,0,3,2] row_mask:0xf bank_mask:0xf bound_ctrl:1
	v_cndmask_b32_e64 v84, v93, v83, s[0:1]
	v_cndmask_b32_e64 v82, v83, v82, s[0:1]
	v_cvt_pk_bf16_f32 v84, v82, v84
	global_store_dword v244, v84, s[100:101] offset:2048
	v_mov_b32_e32 v82, v95
	v_mfma_f32_32x32x16_bf16 v[34:49], v[224:227], v[98:101], v[34:49]
	v_cndmask_b32_e64 v83, v94, v82, s[0:1]
	s_nop 1
	v_mov_b32_dpp v83, v83 quad_perm:[1,0,3,2] row_mask:0xf bank_mask:0xf bound_ctrl:1
	v_cndmask_b32_e64 v82, v82, v83, s[0:1]
	v_cndmask_b32_e64 v83, v83, v94, s[0:1]
	v_cvt_pk_bf16_f32 v84, v83, v82
	s_add_u32 s100, s98, 0xc800
	s_addc_u32 s101, s99, 0
	global_store_dword v244, v84, s[100:101] offset:-2048
	v_mov_b32_e32 v82, v96
	v_mfma_f32_32x32x16_bf16 v[50:65], v[228:231], v[98:101], v[50:65]
	v_cndmask_b32_e64 v83, v82, v97, s[0:1]
	s_nop 1
	v_mov_b32_dpp v83, v83 quad_perm:[1,0,3,2] row_mask:0xf bank_mask:0xf bound_ctrl:1
	v_cndmask_b32_e64 v84, v97, v83, s[0:1]
	v_cndmask_b32_e64 v82, v83, v82, s[0:1]
	v_cvt_pk_bf16_f32 v84, v82, v84
	global_store_dword v244, v84, s[100:101] offset:2048
	s_or_b32 s23, s23, 32
	v_cndmask_b32_e64 v82, v66, v67, s[0:1]
	s_nop 0
	v_mov_b32_dpp v82, v82 quad_perm:[1,0,3,2] row_mask:0xf bank_mask:0xf bound_ctrl:1
	v_cndmask_b32_e64 v67, v67, v82, s[0:1]
	v_cndmask_b32_e64 v66, v82, v66, s[0:1]
	v_cvt_pk_bf16_f32 v82, v66, v67
	s_add_u32 s100, s98, 0x10800
	s_addc_u32 s101, s99, 0
	global_store_dword v244, v82, s[100:101] offset:-2048
	v_mov_b32_e32 v66, v69
	s_nop 0
	v_cndmask_b32_e64 v67, v68, v66, s[0:1]
	s_nop 1
	v_mov_b32_dpp v67, v67 quad_perm:[1,0,3,2] row_mask:0xf bank_mask:0xf bound_ctrl:1
	v_cndmask_b32_e64 v66, v66, v67, s[0:1]
	v_cndmask_b32_e64 v67, v67, v68, s[0:1]
	v_cvt_pk_bf16_f32 v68, v67, v66
	global_store_dword v244, v68, s[100:101] offset:2048
	v_mov_b32_e32 v66, v70
	s_nop 0
	v_cndmask_b32_e64 v67, v66, v71, s[0:1]
	s_nop 1
	v_mov_b32_dpp v67, v67 quad_perm:[1,0,3,2] row_mask:0xf bank_mask:0xf bound_ctrl:1
	v_cndmask_b32_e64 v68, v71, v67, s[0:1]
	v_cndmask_b32_e64 v66, v67, v66, s[0:1]
	v_cvt_pk_bf16_f32 v68, v66, v68
	s_add_u32 s100, s98, 0x14800
	s_addc_u32 s101, s99, 0
	global_store_dword v244, v68, s[100:101] offset:-2048
	v_mov_b32_e32 v66, v72
	s_nop 0
	v_cndmask_b32_e64 v67, v66, v73, s[0:1]
	s_nop 1
	v_mov_b32_dpp v67, v67 quad_perm:[1,0,3,2] row_mask:0xf bank_mask:0xf bound_ctrl:1
	v_cndmask_b32_e64 v68, v73, v67, s[0:1]
	v_cndmask_b32_e64 v66, v67, v66, s[0:1]
	v_cvt_pk_bf16_f32 v68, v66, v68
	global_store_dword v244, v68, s[100:101] offset:2048
	v_mov_b32_e32 v66, v75
	s_nop 0
	v_cndmask_b32_e64 v67, v74, v66, s[0:1]
	s_nop 1
	v_mov_b32_dpp v67, v67 quad_perm:[1,0,3,2] row_mask:0xf bank_mask:0xf bound_ctrl:1
	v_cndmask_b32_e64 v66, v66, v67, s[0:1]
	v_cndmask_b32_e64 v67, v67, v74, s[0:1]
	v_cvt_pk_bf16_f32 v68, v67, v66
	s_add_u32 s100, s98, 0x18800
	s_addc_u32 s101, s99, 0
	global_store_dword v244, v68, s[100:101] offset:-2048
	v_mov_b32_e32 v66, v77
	s_nop 0
	v_cndmask_b32_e64 v67, v76, v66, s[0:1]
	s_nop 1
	v_mov_b32_dpp v67, v67 quad_perm:[1,0,3,2] row_mask:0xf bank_mask:0xf bound_ctrl:1
	v_cndmask_b32_e64 v66, v66, v67, s[0:1]
	v_cndmask_b32_e64 v67, v67, v76, s[0:1]
	v_cvt_pk_bf16_f32 v68, v67, v66
	global_store_dword v244, v68, s[100:101] offset:2048
	v_mov_b32_e32 v66, v78
	s_nop 0
	v_cndmask_b32_e64 v67, v66, v79, s[0:1]
	s_nop 1
	v_mov_b32_dpp v67, v67 quad_perm:[1,0,3,2] row_mask:0xf bank_mask:0xf bound_ctrl:1
	v_cndmask_b32_e64 v68, v79, v67, s[0:1]
	v_cndmask_b32_e64 v66, v67, v66, s[0:1]
	v_cvt_pk_bf16_f32 v68, v66, v68
	s_add_u32 s100, s98, 0x1c800
	s_addc_u32 s101, s99, 0
	global_store_dword v244, v68, s[100:101] offset:-2048
	v_mov_b32_e32 v66, v81
	s_nop 0
	v_cndmask_b32_e64 v67, v80, v66, s[0:1]
	s_nop 1
	v_mov_b32_dpp v67, v67 quad_perm:[1,0,3,2] row_mask:0xf bank_mask:0xf bound_ctrl:1
	v_cndmask_b32_e64 v66, v66, v67, s[0:1]
	v_cndmask_b32_e64 v67, v67, v80, s[0:1]
	v_cvt_pk_bf16_f32 v68, v67, v66
	global_store_dword v244, v68, s[100:101] offset:2048
	s_cmp_eq_u32 s8, -2
	s_cbranch_scc1 .LBB0_965
.LBB0_972:
	s_add_i32 s83, s82, -1
	s_waitcnt vmcnt(16)
	s_barrier
	s_and_b32 s84, s83, 1
	s_cmp_eq_u32 s8, -1
	s_cbranch_scc1 .LBB0_971
	s_and_b64 s[22:23], s[10:11], exec
	s_cselect_b32 s22, s82, s8
	s_add_i32 s22, s22, s81
	s_lshl_b32 s22, s22, 2
	s_or_b32 s86, s22, s80
	s_ashr_i32 s87, s86, 31
	s_add_u32 s22, s25, s86
	s_addc_u32 s23, 0, s87
	s_mul_i32 s64, s23, 0xa000
	s_mul_hi_u32 s65, s22, 0xa000
	s_add_i32 s65, s65, s64
	s_mul_i32 s64, s22, 0xa000
	s_add_u32 s64, s27, s64
	s_addc_u32 s65, s28, s65
	s_lshl_b64 s[86:87], s[86:87], 15
	s_add_u32 s66, s29, s86
	s_addc_u32 s67, s30, s87
	s_xor_b32 s68, s84, 1
	s_mul_i32 s68, s68, 0x12400
	s_add_i32 s85, s68, 0
	v_add_u32_e32 v245, 0x400, v134
	v_add_u32_e32 v246, 0x800, v134
	v_add_u32_e32 v247, 0xc00, v134
	v_add_u32_e32 v248, 0x1000, v134
	s_lshl_b32 s32, s31, 4
	s_lshl_b32 s98, s31, 2
	s_add_i32 s98, s98, s32
	s_add_u32 s100, s64, s98
	s_addc_u32 s101, s65, 0
	s_add_i32 s99, s85, s98
	s_add_u32 s88, s66, s32
	s_addc_u32 s89, s67, 0
	s_add_i32 s90, s85, s32
	s_cmp_ge_u32 s31, 0x400
	s_cbranch_scc1 .Lhalf_t_1
	s_add_i32 m0, s99, 0x0
	s_nop 0
	global_load_lds_dwordx4 v134, s[100:101] nt
	s_add_i32 m0, s99, 0x400
	s_nop 0
	global_load_lds_dwordx4 v245, s[100:101] nt
	s_add_i32 m0, s99, 0x800
	s_nop 0
	global_load_lds_dwordx4 v246, s[100:101] nt
	s_add_i32 m0, s99, 0xc00
	s_nop 0
	global_load_lds_dwordx4 v247, s[100:101] nt
	s_add_i32 m0, s99, 0x1000
	s_nop 0
	global_load_lds_dwordx4 v248, s[100:101] nt
	s_add_i32 m0, s90, 0xa000
	s_nop 0
	global_load_lds_dwordx4 v134, s[88:89] nt
	s_add_i32 m0, s90, 0xa400
	s_nop 0
	global_load_lds_dwordx4 v245, s[88:89] nt
	s_add_i32 m0, s90, 0xa800
	s_nop 0
	global_load_lds_dwordx4 v246, s[88:89] nt
	s_add_i32 m0, s90, 0xac00
	s_nop 0
	global_load_lds_dwordx4 v247, s[88:89] nt
.Lhalf_t_1:
	s_and_b64 vcc, exec, s[2:3]
	s_cbranch_vccnz .LBB0_971
	s_add_i32 s64, s85, s31
	s_lshl_b64 s[22:23], s[22:23], 9
	s_add_i32 m0, s64, 0x12000
	v_lshl_add_u64 v[66:67], v[156:157], 0, s[22:23]
	global_load_lds_dword v[66:67], off
	s_branch .LBB0_971
